# spatial-gating item: second batch of global loads (u_b/z_b gate rows, bias, LayerNorm weights) issued at the item start into free registers, overlapping the first batch
# baseline (speedup 1.0000x reference)
.LBB0_711:
	s_cmpk_gt_i32 s38, 0xff
	s_mov_b64 s[0:1], -1
	s_movk_i32 s13, 0x110
	s_cbranch_scc0 .LBB0_731
	v_mov_b32_e32 v55, v200
	s_add_i32 s0, s38, 0xffffff00
	s_lshr_b32 s2, s0, 3
	v_readfirstlane_b32 s1, v55
	s_and_b32 s0, s38, 7
	s_ashr_i32 s1, s1, 2
	s_lshl_b32 s3, s2, 10
	s_lshl_b32 s7, s0, 7
	s_and_b32 s12, s1, -16
	s_or_b32 s3, s3, s7
	s_ashr_i32 s1, s12, 31
	s_add_u32 s3, s12, s3
	v_and_b32_e32 v68, 15, v55
	s_addc_u32 s1, s1, 0
	v_or_b32_e32 v2, s3, v68
	v_mov_b32_e32 v3, s1
	v_readlane_b32 s40, v252, 49
	v_lshlrev_b64 v[2:3], 8, v[2:3]
	v_readlane_b32 s41, v252, 50
	s_or_b32 s76, s0, s14
	s_lshl_b64 s[0:1], s[76:77], 16
	v_lshl_add_u64 v[2:3], s[40:41], 0, v[2:3]
	v_readlane_b32 s40, v250, 10
	v_readlane_b32 s46, v250, 16
	v_readlane_b32 s47, v250, 17
	s_add_u32 s0, s46, s0
	v_lshlrev_b32_e32 v20, 2, v55
	v_lshlrev_b32_e32 v18, 4, v55
	v_bfe_u32 v54, v55, 4, 2
	s_addc_u32 s1, s47, s1
	v_and_b32_e32 v18, 0x1f0, v18
	v_mov_b32_e32 v19, v1
	v_and_b32_e32 v20, 0xffffff80, v20
	v_lshlrev_b32_e32 v0, 4, v54
	v_lshl_add_u64 v[18:19], s[0:1], 0, v[18:19]
	v_ashrrev_i32_e32 v21, 31, v20
	v_add_u32_e32 v24, 0x800, v20
	v_lshl_add_u64 v[2:3], v[2:3], 0, v[0:1]
	v_lshl_add_u64 v[22:23], v[20:21], 2, v[18:19]
	v_ashrrev_i32_e32 v25, 31, v24
	global_load_dwordx4 v[14:17], v[2:3], off
	global_load_dwordx4 v[10:13], v[2:3], off offset:64
	global_load_dwordx4 v[6:9], v[2:3], off offset:128
	s_nop 0
	global_load_dwordx4 v[2:5], v[2:3], off offset:192
	v_lshl_add_u64 v[24:25], v[24:25], 2, v[18:19]
	global_load_dwordx4 v[46:49], v[22:23], off
	global_load_dwordx4 v[42:45], v[24:25], off
	v_add_u32_e32 v22, 0x1000, v20
	v_ashrrev_i32_e32 v23, 31, v22
	v_add_u32_e32 v24, 0x1800, v20
	v_lshl_add_u64 v[22:23], v[22:23], 2, v[18:19]
	v_ashrrev_i32_e32 v25, 31, v24
	v_lshl_add_u64 v[24:25], v[24:25], 2, v[18:19]
	global_load_dwordx4 v[38:41], v[22:23], off
	global_load_dwordx4 v[34:37], v[24:25], off
	v_add_u32_e32 v22, 0x2000, v20
	v_ashrrev_i32_e32 v23, 31, v22
	v_add_u32_e32 v24, 0x2800, v20
	v_lshl_add_u64 v[22:23], v[22:23], 2, v[18:19]
	v_ashrrev_i32_e32 v25, 31, v24
	v_lshl_add_u64 v[24:25], v[24:25], 2, v[18:19]
	global_load_dwordx4 v[30:33], v[22:23], off
	global_load_dwordx4 v[26:29], v[24:25], off
	v_add_u32_e32 v22, 0x3000, v20
	v_add_u32_e32 v20, 0x3800, v20
	v_ashrrev_i32_e32 v23, 31, v22
	v_ashrrev_i32_e32 v21, 31, v20
	v_lshl_add_u64 v[22:23], v[22:23], 2, v[18:19]
	v_lshl_add_u64 v[18:19], v[20:21], 2, v[18:19]
	global_load_dwordx4 v[22:25], v[22:23], off
	s_nop 0
	global_load_dwordx4 v[18:21], v[18:19], off
	s_movk_i32 s0, 0x80
	s_lshl_b32 s6, s2, 7
	v_cmp_gt_i32_e32 vcc, s0, v55
	v_readlane_b32 s41, v250, 11
	v_readlane_b32 s42, v250, 12
	v_readlane_b32 s43, v250, 13
	v_readlane_b32 s44, v250, 14
	v_readlane_b32 s45, v250, 15
	s_add_i32 s98, s12, s7
	v_or_b32_e32 v194, s6, v68
	v_lshl_or_b32 v195, v54, 2, s98
	v_mul_u32_u24_e32 v196, 0x3500, v194
	v_add_lshl_u32 v196, v196, v195, 1
	v_readlane_b32 s98, v252, 53
	v_readlane_b32 s99, v252, 54
	v_mov_b32_e32 v198, s76
	v_lshlrev_b32_e32 v198, 9, v198
	v_lshl_add_u32 v198, v68, 2, v198
	v_lshlrev_b32_e32 v199, 2, v195
	v_add_u32_e32 v197, 0x1000, v196
	global_load_dwordx2 v[144:145], v197, s[98:99]
	v_add_u32_e32 v197, 0x2000, v196
	global_load_dwordx2 v[146:147], v197, s[98:99]
	v_add_u32_e32 v197, 0x6b000, v196
	global_load_dwordx2 v[148:149], v197, s[98:99]
	v_add_u32_e32 v197, 0x6c000, v196
	global_load_dwordx2 v[150:151], v197, s[98:99]
	v_add_u32_e32 v197, 0xd5000, v196
	global_load_dwordx2 v[152:153], v197, s[98:99]
	v_add_u32_e32 v197, 0xd6000, v196
	global_load_dwordx2 v[154:155], v197, s[98:99]
	v_add_u32_e32 v197, 0x13f000, v196
	global_load_dwordx2 v[156:157], v197, s[98:99]
	v_add_u32_e32 v197, 0x140000, v196
	global_load_dwordx2 v[158:159], v197, s[98:99]
	v_add_u32_e32 v197, 0x1a9000, v196
	global_load_dwordx2 v[160:161], v197, s[98:99]
	v_add_u32_e32 v197, 0x1aa000, v196
	global_load_dwordx2 v[162:163], v197, s[98:99]
	v_add_u32_e32 v197, 0x213000, v196
	global_load_dwordx2 v[164:165], v197, s[98:99]
	v_add_u32_e32 v197, 0x214000, v196
	global_load_dwordx2 v[166:167], v197, s[98:99]
	v_add_u32_e32 v197, 0x27d000, v196
	global_load_dwordx2 v[168:169], v197, s[98:99]
	v_add_u32_e32 v197, 0x27e000, v196
	global_load_dwordx2 v[170:171], v197, s[98:99]
	v_add_u32_e32 v197, 0x2e7000, v196
	global_load_dwordx2 v[172:173], v197, s[98:99]
	v_add_u32_e32 v197, 0x2e8000, v196
	global_load_dwordx2 v[174:175], v197, s[98:99]
	global_load_dwordx4 v[186:189], v199, s[8:9]
	global_load_dwordx4 v[190:193], v199, s[10:11]
	v_readlane_b32 s98, v250, 6
	v_readlane_b32 s99, v250, 7
	s_nop 4
	global_load_dword v178, v198, s[98:99]
	global_load_dword v179, v198, s[98:99] offset:64
	global_load_dword v180, v198, s[98:99] offset:128
	global_load_dword v181, v198, s[98:99] offset:192
	global_load_dword v182, v198, s[98:99] offset:256
	global_load_dword v183, v198, s[98:99] offset:320
	global_load_dword v184, v198, s[98:99] offset:384
	global_load_dword v185, v198, s[98:99] offset:448
	s_and_saveexec_b64 s[2:3], vcc
	s_cbranch_execz .LBB0_714
	v_add_u32_e32 v50, s6, v55
	v_ashrrev_i32_e32 v51, 31, v50
	v_lshl_add_u64 v[50:51], v[50:51], 3, s[4:5]
	global_load_dwordx2 v[50:51], v[50:51], off
	s_mov_b32 s0, 0x3a800000
	s_waitcnt vmcnt(0)
	v_mul_f32_e32 v50, 0x3a800000, v50
	v_mul_f32_e32 v52, v50, v50
	v_fma_f32 v51, v51, s0, -v52
	v_max_f32_e32 v51, 0, v51
	v_add_f32_e32 v51, 0x358637bd, v51
	s_mov_b32 s0, 0xf800000
	v_mul_f32_e32 v52, 0x4f800000, v51
	v_cmp_gt_f32_e32 vcc, s0, v51
	s_nop 1
	v_cndmask_b32_e32 v51, v51, v52, vcc
	v_sqrt_f32_e32 v52, v51
	s_nop 0
	v_add_u32_e32 v53, -1, v52
	v_add_u32_e32 v56, 1, v52
	v_fma_f32 v57, -v53, v52, v51
	v_fma_f32 v58, -v56, v52, v51
	v_cmp_ge_f32_e64 s[0:1], 0, v57
	s_nop 1
	v_cndmask_b32_e64 v52, v52, v53, s[0:1]
	v_cmp_lt_f32_e64 s[0:1], 0, v58
	s_nop 1
	v_cndmask_b32_e64 v52, v52, v56, s[0:1]
	v_mul_f32_e32 v53, 0x37800000, v52
	v_cndmask_b32_e32 v52, v52, v53, vcc
	v_cmp_class_f32_e32 vcc, v51, v220
	v_lshl_add_u32 v56, v55, 3, 0
	s_nop 0
	v_cndmask_b32_e32 v51, v52, v51, vcc
	v_div_scale_f32 v52, s[0:1], v51, v51, 1.0
	v_rcp_f32_e32 v53, v52
	v_div_scale_f32 v57, vcc, 1.0, v51, 1.0
	v_fma_f32 v58, -v52, v53, 1.0
	v_fmac_f32_e32 v53, v58, v53
	v_mul_f32_e32 v58, v57, v53
	v_fma_f32 v59, -v52, v58, v57
	v_fmac_f32_e32 v58, v59, v53
	v_fma_f32 v52, -v52, v58, v57
	v_div_fmas_f32 v52, v52, v53, v58
	v_div_fixup_f32 v51, v52, v51, 1.0
	ds_write_b64 v56, v[50:51]
.LBB0_714:
	s_or_b64 exec, exec, s[2:3]
	v_and_b32_e32 v63, 31, v55
	v_lshl_add_u32 v57, v63, 5, 0
	v_and_b32_e32 v50, 64, v217
	s_waitcnt lgkmcnt(0)
	s_barrier
	v_add_u32_e32 v69, 64, v50
	ds_read_b128 v[50:53], v57
	ds_read_b128 v[58:61], v57 offset:16
	v_lshlrev_b32_e32 v56, 2, v63
	v_ashrrev_i32_e32 v62, 5, v55
	v_cmp_ge_i32_e32 vcc, v62, v56
	s_movk_i32 s0, 0xffe8
	s_waitcnt vmcnt(33)
	v_cndmask_b32_e32 v65, 0, v46, vcc
	v_cmp_lt_i32_e32 vcc, v56, v62
	s_waitcnt lgkmcnt(1)
	v_mov_b32_e32 v46, v53
	v_cndmask_b32_e32 v64, 0, v47, vcc
	v_mov_b32_e32 v47, v51
	v_pk_mul_f32 v[46:47], v[64:65], v[46:47]
	s_nop 0
	v_and_b32_sdwa v51, v47, v221 dst_sel:DWORD dst_unused:UNUSED_PAD src0_sel:WORD_1 src1_sel:DWORD
	v_and_b32_sdwa v53, v46, v221 dst_sel:DWORD dst_unused:UNUSED_PAD src0_sel:WORD_1 src1_sel:DWORD
	v_add3_u32 v72, v47, v51, s23
	v_add3_u32 v46, v46, v53, s23
	v_or_b32_e32 v47, 3, v56
	v_and_b32_e32 v67, 0xffff0000, v46
	v_or_b32_e32 v46, 2, v56
	v_cmp_le_i32_e32 vcc, v47, v62
	v_and_b32_e32 v66, 0xffff0000, v72
	s_nop 0
	v_cndmask_b32_e32 v71, 0, v49, vcc
	v_cmp_le_i32_e32 vcc, v46, v62
	s_waitcnt lgkmcnt(0)
	v_mov_b32_e32 v49, v61
	v_cndmask_b32_e32 v70, 0, v48, vcc
	v_mov_b32_e32 v48, v59
	v_pk_mul_f32 v[48:49], v[70:71], v[48:49]
	s_nop 0
	v_and_b32_sdwa v51, v49, v221 dst_sel:DWORD dst_unused:UNUSED_PAD src0_sel:WORD_1 src1_sel:DWORD
	v_and_b32_sdwa v53, v48, v221 dst_sel:DWORD dst_unused:UNUSED_PAD src0_sel:WORD_1 src1_sel:DWORD
	v_add3_u32 v49, v49, v51, s23
	v_add3_u32 v73, v48, v53, s23
	v_mov_b32_e32 v51, v52
	v_mul_f32_e32 v48, v52, v67
	v_and_b32_e32 v74, 0xffff0000, v49
	v_pk_fma_f32 v[50:51], v[50:51], v[66:67], v[48:49] op_sel_hi:[1,1,0]
	v_and_b32_e32 v48, 0xffff0000, v73
	v_mov_b32_e32 v49, v64
	v_mul_f32_e32 v52, v58, v48
	v_mul_f32_e32 v58, v60, v74
	v_pk_add_f32 v[60:61], v[64:65], v[48:49]
	v_xor_b32_e32 v48, 1, v217
	v_cmp_lt_i32_e32 vcc, v48, v69
	v_mov_b32_e32 v51, v70
	v_mov_b32_e32 v53, v71
	v_cndmask_b32_e32 v48, v217, v48, vcc
	v_pk_add_f32 v[50:51], v[50:51], v[52:53]
	v_mov_b32_e32 v59, v61
	v_lshlrev_b32_e32 v49, 2, v48
	v_pk_add_f32 v[50:51], v[58:59], v[50:51]
	v_mov_b32_e32 v110, v50
	v_mov_b32_e32 v111, v51
	v_xor_b32_e32 v48, 2, v217
	v_cmp_lt_i32_e32 vcc, v48, v69
	v_or_b32_sdwa v64, v67, v72 dst_sel:DWORD dst_unused:UNUSED_PAD src0_sel:DWORD src1_sel:WORD_1
	v_or_b32_sdwa v65, v74, v73 dst_sel:DWORD dst_unused:UNUSED_PAD src0_sel:DWORD src1_sel:WORD_1
	v_cndmask_b32_e32 v48, v217, v48, vcc
	v_lshlrev_b32_e32 v58, 2, v48
	v_xor_b32_e32 v48, 4, v217
	v_cmp_lt_i32_e32 vcc, v48, v69
	v_cndmask_b32_e32 v48, v217, v48, vcc
	v_lshlrev_b32_e32 v59, 2, v48
	v_xor_b32_e32 v48, 8, v217
	v_cmp_lt_i32_e32 vcc, v48, v69
	v_cndmask_b32_e32 v48, v217, v48, vcc
	v_lshlrev_b32_e32 v60, 2, v48
	v_mad_i32_i24 v48, v63, s0, v57
	v_cmp_eq_u32_e32 vcc, 0, v63
	v_xor_b32_e32 v52, 16, v217
	v_cmp_lt_i32_e64 s[0:1], v52, v69
	s_nop 1
	v_cndmask_b32_e64 v52, v217, v52, s[0:1]
	v_lshlrev_b32_e32 v61, 2, v52
	v_mad_u64_u32 v[66:67], s[0:1], v62, s13, v[48:49]
	ds_write_b64 v66, v[64:65] offset:2048
	v_add_u32_e32 v50, 0x200, v55
	ds_read_b128 v[62:65], v57
	ds_read_b128 v[70:73], v57 offset:16
	v_ashrrev_i32_e32 v50, 5, v50
	v_cmp_ge_i32_e64 s[0:1], v50, v46
	s_waitcnt lgkmcnt(1)
	v_mov_b32_e32 v66, v63
	s_waitcnt vmcnt(32)
	v_cndmask_b32_e64 v53, 0, v44, s[0:1]
	v_cmp_lt_i32_e64 s[0:1], v56, v50
	v_mov_b32_e32 v44, v65
	s_waitcnt lgkmcnt(0)
	v_mov_b32_e32 v67, v73
	v_cndmask_b32_e64 v52, 0, v43, s[0:1]
	v_cmp_le_i32_e64 s[0:1], v47, v50
	s_nop 1
	v_cndmask_b32_e64 v43, 0, v45, s[0:1]
	v_mov_b32_e32 v45, v71
	v_cmp_le_i32_e64 s[0:1], v56, v50
	v_pk_mul_f32 v[44:45], v[52:53], v[44:45]
	s_nop 0
	v_cndmask_b32_e64 v42, 0, v42, s[0:1]
	v_and_b32_sdwa v63, v44, v221 dst_sel:DWORD dst_unused:UNUSED_PAD src0_sel:WORD_1 src1_sel:DWORD
	v_pk_mul_f32 v[66:67], v[42:43], v[66:67]
	v_and_b32_sdwa v51, v45, v221 dst_sel:DWORD dst_unused:UNUSED_PAD src0_sel:WORD_1 src1_sel:DWORD
	v_add3_u32 v44, v44, v63, s23
	v_add3_u32 v51, v45, v51, s23
	v_and_b32_e32 v75, 0xffff0000, v44
	v_and_b32_sdwa v44, v67, v221 dst_sel:DWORD dst_unused:UNUSED_PAD src0_sel:WORD_1 src1_sel:DWORD
	v_and_b32_sdwa v45, v66, v221 dst_sel:DWORD dst_unused:UNUSED_PAD src0_sel:WORD_1 src1_sel:DWORD
	v_add3_u32 v44, v67, v44, s23
	v_add3_u32 v69, v66, v45, s23
	v_and_b32_e32 v71, 0xffff0000, v44
	v_and_b32_e32 v74, 0xffff0000, v69
	v_mov_b32_e32 v63, v64
	v_mul_f32_e32 v44, v64, v75
	v_pk_fma_f32 v[44:45], v[62:63], v[74:75], v[44:45] op_sel_hi:[1,1,0]
	v_pk_add_f32 v[66:67], v[42:43], v[52:53]
	v_and_b32_e32 v45, 0xffff0000, v51
	v_mul_f32_e32 v62, v70, v45
	v_mov_b32_e32 v45, v53
	v_mov_b32_e32 v63, v43
	v_mul_f32_e32 v64, v72, v71
	v_pk_add_f32 v[42:43], v[44:45], v[62:63]
	v_mov_b32_e32 v65, v66
	v_pk_add_f32 v[42:43], v[64:65], v[42:43]
	v_mov_b32_e32 v112, v42
	v_mov_b32_e32 v113, v43
	v_or_b32_sdwa v53, v71, v51 dst_sel:DWORD dst_unused:UNUSED_PAD src0_sel:DWORD src1_sel:WORD_1
	v_or_b32_sdwa v52, v69, v75 dst_sel:DWORD dst_unused:UNUSED_PAD src0_sel:WORD_1 src1_sel:DWORD
	v_mad_u64_u32 v[62:63], s[0:1], v50, s13, v[48:49]
	ds_write_b64 v62, v[52:53] offset:2048
	v_add_u32_e32 v42, 0x400, v55
	ds_read_b128 v[50:53], v57
	ds_read_b128 v[62:65], v57 offset:16
	v_ashrrev_i32_e32 v42, 5, v42
	v_cmp_ge_i32_e64 s[0:1], v42, v46
	s_waitcnt lgkmcnt(1)
	v_mov_b32_e32 v66, v51
	s_waitcnt vmcnt(31)
	v_cndmask_b32_e64 v45, 0, v40, s[0:1]
	v_cmp_lt_i32_e64 s[0:1], v56, v42
	v_mov_b32_e32 v40, v53
	s_waitcnt lgkmcnt(0)
	v_mov_b32_e32 v67, v65
	v_cndmask_b32_e64 v44, 0, v39, s[0:1]
	v_cmp_le_i32_e64 s[0:1], v47, v42
	s_nop 1
	v_cndmask_b32_e64 v39, 0, v41, s[0:1]
	v_mov_b32_e32 v41, v63
	v_cmp_le_i32_e64 s[0:1], v56, v42
	v_pk_mul_f32 v[40:41], v[44:45], v[40:41]
	s_nop 0
	v_cndmask_b32_e64 v38, 0, v38, s[0:1]
	v_and_b32_sdwa v51, v40, v221 dst_sel:DWORD dst_unused:UNUSED_PAD src0_sel:WORD_1 src1_sel:DWORD
	v_pk_mul_f32 v[66:67], v[38:39], v[66:67]
	v_and_b32_sdwa v43, v41, v221 dst_sel:DWORD dst_unused:UNUSED_PAD src0_sel:WORD_1 src1_sel:DWORD
	v_add3_u32 v40, v40, v51, s23
	v_add3_u32 v43, v41, v43, s23
	v_and_b32_e32 v71, 0xffff0000, v40
	v_and_b32_sdwa v40, v67, v221 dst_sel:DWORD dst_unused:UNUSED_PAD src0_sel:WORD_1 src1_sel:DWORD
	v_and_b32_sdwa v41, v66, v221 dst_sel:DWORD dst_unused:UNUSED_PAD src0_sel:WORD_1 src1_sel:DWORD
	v_add3_u32 v40, v67, v40, s23
	v_add3_u32 v65, v66, v41, s23
	v_and_b32_e32 v66, 0xffff0000, v40
	v_and_b32_e32 v70, 0xffff0000, v65
	v_mov_b32_e32 v51, v52
	v_mul_f32_e32 v40, v52, v71
	v_pk_fma_f32 v[40:41], v[50:51], v[70:71], v[40:41] op_sel_hi:[1,1,0]
	v_mov_b32_e32 v51, v39
	v_and_b32_e32 v41, 0xffff0000, v43
	v_mul_f32_e32 v50, v62, v41
	v_pk_add_f32 v[62:63], v[38:39], v[44:45]
	v_mov_b32_e32 v41, v45
	v_mul_f32_e32 v52, v64, v66
	v_pk_add_f32 v[38:39], v[40:41], v[50:51]
	v_mov_b32_e32 v53, v62
	v_pk_add_f32 v[38:39], v[52:53], v[38:39]
	v_mov_b32_e32 v114, v38
	v_mov_b32_e32 v115, v39
	v_or_b32_sdwa v45, v66, v43 dst_sel:DWORD dst_unused:UNUSED_PAD src0_sel:DWORD src1_sel:WORD_1
	v_or_b32_sdwa v44, v65, v71 dst_sel:DWORD dst_unused:UNUSED_PAD src0_sel:WORD_1 src1_sel:DWORD
	v_mad_u64_u32 v[50:51], s[0:1], v42, s13, v[48:49]
	ds_write_b64 v50, v[44:45] offset:2048
	v_add_u32_e32 v38, 0x600, v55
	s_waitcnt lgkmcnt(0)
	ds_read_b128 v[40:43], v57
	ds_read_b128 v[50:53], v57 offset:16
	v_ashrrev_i32_e32 v38, 5, v38
	v_cmp_ge_i32_e64 s[0:1], v38, v46
	s_waitcnt lgkmcnt(1)
	v_mov_b32_e32 v62, v41
	s_waitcnt vmcnt(30)
	v_cndmask_b32_e64 v45, 0, v36, s[0:1]
	v_cmp_lt_i32_e64 s[0:1], v56, v38
	v_mov_b32_e32 v36, v43
	s_waitcnt lgkmcnt(0)
	v_mov_b32_e32 v63, v53
	v_cndmask_b32_e64 v44, 0, v35, s[0:1]
	v_cmp_le_i32_e64 s[0:1], v47, v38
	s_nop 1
	v_cndmask_b32_e64 v35, 0, v37, s[0:1]
	v_mov_b32_e32 v37, v51
	v_cmp_le_i32_e64 s[0:1], v56, v38
	v_pk_mul_f32 v[36:37], v[44:45], v[36:37]
	s_nop 0
	v_cndmask_b32_e64 v34, 0, v34, s[0:1]
	v_and_b32_sdwa v41, v36, v221 dst_sel:DWORD dst_unused:UNUSED_PAD src0_sel:WORD_1 src1_sel:DWORD
	v_pk_mul_f32 v[62:63], v[34:35], v[62:63]
	v_and_b32_sdwa v39, v37, v221 dst_sel:DWORD dst_unused:UNUSED_PAD src0_sel:WORD_1 src1_sel:DWORD
	v_add3_u32 v36, v36, v41, s23
	v_add3_u32 v39, v37, v39, s23
	v_and_b32_e32 v65, 0xffff0000, v36
	v_and_b32_sdwa v36, v63, v221 dst_sel:DWORD dst_unused:UNUSED_PAD src0_sel:WORD_1 src1_sel:DWORD
	v_and_b32_sdwa v37, v62, v221 dst_sel:DWORD dst_unused:UNUSED_PAD src0_sel:WORD_1 src1_sel:DWORD
	v_add3_u32 v36, v63, v36, s23
	v_add3_u32 v53, v62, v37, s23
	v_and_b32_e32 v62, 0xffff0000, v36
	v_and_b32_e32 v64, 0xffff0000, v53
	v_mov_b32_e32 v41, v42
	v_mul_f32_e32 v36, v42, v65
	v_pk_fma_f32 v[36:37], v[40:41], v[64:65], v[36:37] op_sel_hi:[1,1,0]
	v_mov_b32_e32 v41, v35
	v_and_b32_e32 v37, 0xffff0000, v39
	v_mul_f32_e32 v40, v50, v37
	v_pk_add_f32 v[50:51], v[34:35], v[44:45]
	v_mov_b32_e32 v37, v45
	v_mul_f32_e32 v42, v52, v62
	v_pk_add_f32 v[34:35], v[36:37], v[40:41]
	v_mov_b32_e32 v43, v50
	v_pk_add_f32 v[34:35], v[42:43], v[34:35]
	v_mov_b32_e32 v116, v34
	v_mov_b32_e32 v117, v35
	v_or_b32_sdwa v41, v62, v39 dst_sel:DWORD dst_unused:UNUSED_PAD src0_sel:DWORD src1_sel:WORD_1
	v_or_b32_sdwa v40, v53, v65 dst_sel:DWORD dst_unused:UNUSED_PAD src0_sel:WORD_1 src1_sel:DWORD
	v_mad_u64_u32 v[42:43], s[0:1], v38, s13, v[48:49]
	ds_write_b64 v42, v[40:41] offset:2048
	v_add_u32_e32 v34, 0x800, v55
	s_waitcnt lgkmcnt(0)
	ds_read_b128 v[36:39], v57
	ds_read_b128 v[40:43], v57 offset:16
	v_ashrrev_i32_e32 v34, 5, v34
	v_cmp_ge_i32_e64 s[0:1], v34, v46
	s_waitcnt lgkmcnt(1)
	v_mov_b32_e32 v50, v37
	s_waitcnt vmcnt(29)
	v_cndmask_b32_e64 v45, 0, v32, s[0:1]
	v_cmp_lt_i32_e64 s[0:1], v56, v34
	v_mov_b32_e32 v32, v39
	s_waitcnt lgkmcnt(0)
	v_mov_b32_e32 v51, v43
	v_cndmask_b32_e64 v44, 0, v31, s[0:1]
	v_cmp_le_i32_e64 s[0:1], v47, v34
	s_nop 1
	v_cndmask_b32_e64 v31, 0, v33, s[0:1]
	v_mov_b32_e32 v33, v41
	v_cmp_le_i32_e64 s[0:1], v56, v34
	v_pk_mul_f32 v[32:33], v[44:45], v[32:33]
	s_nop 0
	v_cndmask_b32_e64 v30, 0, v30, s[0:1]
	v_and_b32_sdwa v37, v32, v221 dst_sel:DWORD dst_unused:UNUSED_PAD src0_sel:WORD_1 src1_sel:DWORD
	v_pk_mul_f32 v[50:51], v[30:31], v[50:51]
	v_and_b32_sdwa v35, v33, v221 dst_sel:DWORD dst_unused:UNUSED_PAD src0_sel:WORD_1 src1_sel:DWORD
	v_add3_u32 v32, v32, v37, s23
	v_add3_u32 v35, v33, v35, s23
	v_and_b32_e32 v53, 0xffff0000, v32
	v_and_b32_sdwa v32, v51, v221 dst_sel:DWORD dst_unused:UNUSED_PAD src0_sel:WORD_1 src1_sel:DWORD
	v_and_b32_sdwa v33, v50, v221 dst_sel:DWORD dst_unused:UNUSED_PAD src0_sel:WORD_1 src1_sel:DWORD
	v_add3_u32 v32, v51, v32, s23
	v_add3_u32 v43, v50, v33, s23
	v_and_b32_e32 v50, 0xffff0000, v32
	v_and_b32_e32 v52, 0xffff0000, v43
	v_mov_b32_e32 v37, v38
	v_mul_f32_e32 v32, v38, v53
	v_pk_fma_f32 v[32:33], v[36:37], v[52:53], v[32:33] op_sel_hi:[1,1,0]
	v_mov_b32_e32 v37, v31
	v_and_b32_e32 v33, 0xffff0000, v35
	v_mul_f32_e32 v36, v40, v33
	v_pk_add_f32 v[40:41], v[30:31], v[44:45]
	v_mov_b32_e32 v33, v45
	v_mul_f32_e32 v38, v42, v50
	v_pk_add_f32 v[30:31], v[32:33], v[36:37]
	v_mov_b32_e32 v39, v40
	v_pk_add_f32 v[30:31], v[38:39], v[30:31]
	v_mov_b32_e32 v118, v30
	v_mov_b32_e32 v119, v31
	v_or_b32_sdwa v37, v50, v35 dst_sel:DWORD dst_unused:UNUSED_PAD src0_sel:DWORD src1_sel:WORD_1
	v_or_b32_sdwa v36, v43, v53 dst_sel:DWORD dst_unused:UNUSED_PAD src0_sel:WORD_1 src1_sel:DWORD
	v_mad_u64_u32 v[38:39], s[0:1], v34, s13, v[48:49]
	ds_write_b64 v38, v[36:37] offset:2048
	v_add_u32_e32 v30, 0xa00, v55
	s_waitcnt lgkmcnt(0)
	ds_read_b128 v[32:35], v57
	ds_read_b128 v[36:39], v57 offset:16
	v_ashrrev_i32_e32 v30, 5, v30
	v_cmp_ge_i32_e64 s[0:1], v30, v46
	s_waitcnt lgkmcnt(1)
	v_mov_b32_e32 v42, v33
	s_waitcnt vmcnt(28)
	v_cndmask_b32_e64 v41, 0, v28, s[0:1]
	v_cmp_lt_i32_e64 s[0:1], v56, v30
	v_mov_b32_e32 v28, v35
	s_waitcnt lgkmcnt(0)
	v_mov_b32_e32 v43, v39
	v_cndmask_b32_e64 v40, 0, v27, s[0:1]
	v_cmp_le_i32_e64 s[0:1], v47, v30
	s_nop 1
	v_cndmask_b32_e64 v27, 0, v29, s[0:1]
	v_mov_b32_e32 v29, v37
	v_cmp_le_i32_e64 s[0:1], v56, v30
	v_pk_mul_f32 v[28:29], v[40:41], v[28:29]
	s_nop 0
	v_cndmask_b32_e64 v26, 0, v26, s[0:1]
	v_and_b32_sdwa v33, v28, v221 dst_sel:DWORD dst_unused:UNUSED_PAD src0_sel:WORD_1 src1_sel:DWORD
	v_pk_mul_f32 v[42:43], v[26:27], v[42:43]
	v_and_b32_sdwa v31, v29, v221 dst_sel:DWORD dst_unused:UNUSED_PAD src0_sel:WORD_1 src1_sel:DWORD
	v_add3_u32 v28, v28, v33, s23
	v_add3_u32 v31, v29, v31, s23
	v_and_b32_e32 v45, 0xffff0000, v28
	v_and_b32_sdwa v28, v43, v221 dst_sel:DWORD dst_unused:UNUSED_PAD src0_sel:WORD_1 src1_sel:DWORD
	v_and_b32_sdwa v29, v42, v221 dst_sel:DWORD dst_unused:UNUSED_PAD src0_sel:WORD_1 src1_sel:DWORD
	v_add3_u32 v28, v43, v28, s23
	v_add3_u32 v39, v42, v29, s23
	v_and_b32_e32 v42, 0xffff0000, v28
	v_and_b32_e32 v44, 0xffff0000, v39
	v_mov_b32_e32 v33, v34
	v_mul_f32_e32 v28, v34, v45
	v_pk_fma_f32 v[28:29], v[32:33], v[44:45], v[28:29] op_sel_hi:[1,1,0]
	v_mov_b32_e32 v33, v27
	v_and_b32_e32 v29, 0xffff0000, v31
	v_mul_f32_e32 v32, v36, v29
	v_pk_add_f32 v[36:37], v[26:27], v[40:41]
	v_mov_b32_e32 v29, v41
	v_mul_f32_e32 v34, v38, v42
	v_pk_add_f32 v[26:27], v[28:29], v[32:33]
	v_mov_b32_e32 v35, v36
	v_pk_add_f32 v[26:27], v[34:35], v[26:27]
	v_mov_b32_e32 v120, v26
	v_mov_b32_e32 v121, v27
	v_or_b32_sdwa v33, v42, v31 dst_sel:DWORD dst_unused:UNUSED_PAD src0_sel:DWORD src1_sel:WORD_1
	v_or_b32_sdwa v32, v39, v45 dst_sel:DWORD dst_unused:UNUSED_PAD src0_sel:WORD_1 src1_sel:DWORD
	v_mad_u64_u32 v[34:35], s[0:1], v30, s13, v[48:49]
	ds_write_b64 v34, v[32:33] offset:2048
	v_add_u32_e32 v26, 0xc00, v55
	s_waitcnt lgkmcnt(0)
	ds_read_b128 v[28:31], v57
	ds_read_b128 v[32:35], v57 offset:16
	v_ashrrev_i32_e32 v26, 5, v26
	v_cmp_ge_i32_e64 s[0:1], v26, v46
	s_waitcnt lgkmcnt(1)
	v_mov_b32_e32 v38, v29
	s_waitcnt vmcnt(27)
	v_cndmask_b32_e64 v37, 0, v24, s[0:1]
	v_cmp_lt_i32_e64 s[0:1], v56, v26
	v_mov_b32_e32 v24, v31
	s_waitcnt lgkmcnt(0)
	v_mov_b32_e32 v39, v35
	v_cndmask_b32_e64 v36, 0, v23, s[0:1]
	v_cmp_le_i32_e64 s[0:1], v47, v26
	s_nop 1
	v_cndmask_b32_e64 v23, 0, v25, s[0:1]
	v_mov_b32_e32 v25, v33
	v_cmp_le_i32_e64 s[0:1], v56, v26
	v_pk_mul_f32 v[24:25], v[36:37], v[24:25]
	s_nop 0
	v_cndmask_b32_e64 v22, 0, v22, s[0:1]
	v_and_b32_sdwa v29, v24, v221 dst_sel:DWORD dst_unused:UNUSED_PAD src0_sel:WORD_1 src1_sel:DWORD
	v_pk_mul_f32 v[38:39], v[22:23], v[38:39]
	v_and_b32_sdwa v27, v25, v221 dst_sel:DWORD dst_unused:UNUSED_PAD src0_sel:WORD_1 src1_sel:DWORD
	v_add3_u32 v24, v24, v29, s23
	v_add3_u32 v27, v25, v27, s23
	v_and_b32_e32 v41, 0xffff0000, v24
	v_and_b32_sdwa v24, v39, v221 dst_sel:DWORD dst_unused:UNUSED_PAD src0_sel:WORD_1 src1_sel:DWORD
	v_and_b32_sdwa v25, v38, v221 dst_sel:DWORD dst_unused:UNUSED_PAD src0_sel:WORD_1 src1_sel:DWORD
	v_add3_u32 v24, v39, v24, s23
	v_add3_u32 v35, v38, v25, s23
	v_and_b32_e32 v38, 0xffff0000, v24
	v_and_b32_e32 v40, 0xffff0000, v35
	v_mov_b32_e32 v29, v30
	v_mul_f32_e32 v24, v30, v41
	v_pk_fma_f32 v[24:25], v[28:29], v[40:41], v[24:25] op_sel_hi:[1,1,0]
	v_mov_b32_e32 v29, v23
	v_and_b32_e32 v25, 0xffff0000, v27
	v_mul_f32_e32 v28, v32, v25
	v_pk_add_f32 v[32:33], v[22:23], v[36:37]
	v_mov_b32_e32 v25, v37
	v_mul_f32_e32 v30, v34, v38
	v_pk_add_f32 v[22:23], v[24:25], v[28:29]
	v_mov_b32_e32 v31, v32
	v_pk_add_f32 v[22:23], v[30:31], v[22:23]
	v_mov_b32_e32 v122, v22
	v_mov_b32_e32 v123, v23
	v_or_b32_sdwa v29, v38, v27 dst_sel:DWORD dst_unused:UNUSED_PAD src0_sel:DWORD src1_sel:WORD_1
	v_or_b32_sdwa v28, v35, v41 dst_sel:DWORD dst_unused:UNUSED_PAD src0_sel:WORD_1 src1_sel:DWORD
	v_mad_u64_u32 v[30:31], s[0:1], v26, s13, v[48:49]
	ds_write_b64 v30, v[28:29] offset:2048
	v_add_u32_e32 v22, 0xe00, v55
	s_waitcnt lgkmcnt(0)
	ds_read_b128 v[24:27], v57
	ds_read_b128 v[28:31], v57 offset:16
	v_ashrrev_i32_e32 v22, 5, v22
	v_cmp_ge_i32_e64 s[0:1], v22, v46
	s_waitcnt lgkmcnt(1)
	v_mov_b32_e32 v34, v25
	s_waitcnt vmcnt(26)
	v_cndmask_b32_e64 v33, 0, v20, s[0:1]
	v_cmp_lt_i32_e64 s[0:1], v56, v22
	v_mov_b32_e32 v20, v27
	s_waitcnt lgkmcnt(0)
	v_mov_b32_e32 v35, v31
	v_cndmask_b32_e64 v32, 0, v19, s[0:1]
	v_cmp_le_i32_e64 s[0:1], v47, v22
	s_nop 1
	v_cndmask_b32_e64 v19, 0, v21, s[0:1]
	v_mov_b32_e32 v21, v29
	v_cmp_le_i32_e64 s[0:1], v56, v22
	v_pk_mul_f32 v[20:21], v[32:33], v[20:21]
	s_nop 0
	v_cndmask_b32_e64 v18, 0, v18, s[0:1]
	v_and_b32_sdwa v25, v20, v221 dst_sel:DWORD dst_unused:UNUSED_PAD src0_sel:WORD_1 src1_sel:DWORD
	v_pk_mul_f32 v[34:35], v[18:19], v[34:35]
	v_and_b32_sdwa v23, v21, v221 dst_sel:DWORD dst_unused:UNUSED_PAD src0_sel:WORD_1 src1_sel:DWORD
	v_add3_u32 v20, v20, v25, s23
	v_add3_u32 v23, v21, v23, s23
	v_and_b32_e32 v37, 0xffff0000, v20
	v_and_b32_sdwa v20, v35, v221 dst_sel:DWORD dst_unused:UNUSED_PAD src0_sel:WORD_1 src1_sel:DWORD
	v_and_b32_sdwa v21, v34, v221 dst_sel:DWORD dst_unused:UNUSED_PAD src0_sel:WORD_1 src1_sel:DWORD
	v_add3_u32 v20, v35, v20, s23
	v_add3_u32 v31, v34, v21, s23
	v_and_b32_e32 v34, 0xffff0000, v20
	v_and_b32_e32 v36, 0xffff0000, v31
	v_mov_b32_e32 v25, v26
	v_mul_f32_e32 v20, v26, v37
	v_pk_fma_f32 v[20:21], v[24:25], v[36:37], v[20:21] op_sel_hi:[1,1,0]
	v_mov_b32_e32 v25, v19
	v_and_b32_e32 v21, 0xffff0000, v23
	v_mul_f32_e32 v24, v28, v21
	v_pk_add_f32 v[28:29], v[18:19], v[32:33]
	v_mov_b32_e32 v21, v33
	v_mul_f32_e32 v26, v30, v34
	v_pk_add_f32 v[18:19], v[20:21], v[24:25]
	v_mov_b32_e32 v27, v28
	v_pk_add_f32 v[18:19], v[26:27], v[18:19]
	v_mov_b32_e32 v124, v18
	v_mov_b32_e32 v125, v19
	v_or_b32_sdwa v25, v34, v23 dst_sel:DWORD dst_unused:UNUSED_PAD src0_sel:DWORD src1_sel:WORD_1
	v_or_b32_sdwa v24, v31, v37 dst_sel:DWORD dst_unused:UNUSED_PAD src0_sel:WORD_1 src1_sel:DWORD
	v_mad_u64_u32 v[26:27], s[0:1], v22, s13, v[48:49]
	ds_write_b64 v26, v[24:25] offset:2048
	ds_bpermute_b32 v126, v49, v110
	ds_bpermute_b32 v127, v49, v111
	ds_bpermute_b32 v128, v49, v112
	ds_bpermute_b32 v129, v49, v113
	ds_bpermute_b32 v130, v49, v114
	ds_bpermute_b32 v131, v49, v115
	ds_bpermute_b32 v132, v49, v116
	ds_bpermute_b32 v133, v49, v117
	s_waitcnt lgkmcnt(0)
	v_pk_add_f32 v[110:111], v[110:111], v[126:127]
	v_pk_add_f32 v[112:113], v[112:113], v[128:129]
	v_pk_add_f32 v[114:115], v[114:115], v[130:131]
	v_pk_add_f32 v[116:117], v[116:117], v[132:133]
	ds_bpermute_b32 v134, v49, v118
	ds_bpermute_b32 v135, v49, v119
	ds_bpermute_b32 v136, v49, v120
	ds_bpermute_b32 v137, v49, v121
	ds_bpermute_b32 v138, v49, v122
	ds_bpermute_b32 v139, v49, v123
	ds_bpermute_b32 v140, v49, v124
	ds_bpermute_b32 v141, v49, v125
	s_waitcnt lgkmcnt(0)
	v_pk_add_f32 v[118:119], v[118:119], v[134:135]
	v_pk_add_f32 v[120:121], v[120:121], v[136:137]
	v_pk_add_f32 v[122:123], v[122:123], v[138:139]
	v_pk_add_f32 v[124:125], v[124:125], v[140:141]
	ds_bpermute_b32 v126, v58, v110
	ds_bpermute_b32 v127, v58, v111
	ds_bpermute_b32 v128, v58, v112
	ds_bpermute_b32 v129, v58, v113
	ds_bpermute_b32 v130, v58, v114
	ds_bpermute_b32 v131, v58, v115
	ds_bpermute_b32 v132, v58, v116
	ds_bpermute_b32 v133, v58, v117
	s_waitcnt lgkmcnt(0)
	v_pk_add_f32 v[110:111], v[110:111], v[126:127]
	v_pk_add_f32 v[112:113], v[112:113], v[128:129]
	v_pk_add_f32 v[114:115], v[114:115], v[130:131]
	v_pk_add_f32 v[116:117], v[116:117], v[132:133]
	ds_bpermute_b32 v134, v58, v118
	ds_bpermute_b32 v135, v58, v119
	ds_bpermute_b32 v136, v58, v120
	ds_bpermute_b32 v137, v58, v121
	ds_bpermute_b32 v138, v58, v122
	ds_bpermute_b32 v139, v58, v123
	ds_bpermute_b32 v140, v58, v124
	ds_bpermute_b32 v141, v58, v125
	s_waitcnt lgkmcnt(0)
	v_pk_add_f32 v[118:119], v[118:119], v[134:135]
	v_pk_add_f32 v[120:121], v[120:121], v[136:137]
	v_pk_add_f32 v[122:123], v[122:123], v[138:139]
	v_pk_add_f32 v[124:125], v[124:125], v[140:141]
	ds_bpermute_b32 v126, v59, v110
	ds_bpermute_b32 v127, v59, v111
	ds_bpermute_b32 v128, v59, v112
	ds_bpermute_b32 v129, v59, v113
	ds_bpermute_b32 v130, v59, v114
	ds_bpermute_b32 v131, v59, v115
	ds_bpermute_b32 v132, v59, v116
	ds_bpermute_b32 v133, v59, v117
	s_waitcnt lgkmcnt(0)
	v_pk_add_f32 v[110:111], v[110:111], v[126:127]
	v_pk_add_f32 v[112:113], v[112:113], v[128:129]
	v_pk_add_f32 v[114:115], v[114:115], v[130:131]
	v_pk_add_f32 v[116:117], v[116:117], v[132:133]
	ds_bpermute_b32 v134, v59, v118
	ds_bpermute_b32 v135, v59, v119
	ds_bpermute_b32 v136, v59, v120
	ds_bpermute_b32 v137, v59, v121
	ds_bpermute_b32 v138, v59, v122
	ds_bpermute_b32 v139, v59, v123
	ds_bpermute_b32 v140, v59, v124
	ds_bpermute_b32 v141, v59, v125
	s_waitcnt lgkmcnt(0)
	v_pk_add_f32 v[118:119], v[118:119], v[134:135]
	v_pk_add_f32 v[120:121], v[120:121], v[136:137]
	v_pk_add_f32 v[122:123], v[122:123], v[138:139]
	v_pk_add_f32 v[124:125], v[124:125], v[140:141]
	ds_bpermute_b32 v126, v60, v110
	ds_bpermute_b32 v127, v60, v111
	ds_bpermute_b32 v128, v60, v112
	ds_bpermute_b32 v129, v60, v113
	ds_bpermute_b32 v130, v60, v114
	ds_bpermute_b32 v131, v60, v115
	ds_bpermute_b32 v132, v60, v116
	ds_bpermute_b32 v133, v60, v117
	s_waitcnt lgkmcnt(0)
	v_pk_add_f32 v[110:111], v[110:111], v[126:127]
	v_pk_add_f32 v[112:113], v[112:113], v[128:129]
	v_pk_add_f32 v[114:115], v[114:115], v[130:131]
	v_pk_add_f32 v[116:117], v[116:117], v[132:133]
	ds_bpermute_b32 v134, v60, v118
	ds_bpermute_b32 v135, v60, v119
	ds_bpermute_b32 v136, v60, v120
	ds_bpermute_b32 v137, v60, v121
	ds_bpermute_b32 v138, v60, v122
	ds_bpermute_b32 v139, v60, v123
	ds_bpermute_b32 v140, v60, v124
	ds_bpermute_b32 v141, v60, v125
	s_waitcnt lgkmcnt(0)
	v_pk_add_f32 v[118:119], v[118:119], v[134:135]
	v_pk_add_f32 v[120:121], v[120:121], v[136:137]
	v_pk_add_f32 v[122:123], v[122:123], v[138:139]
	v_pk_add_f32 v[124:125], v[124:125], v[140:141]
	ds_bpermute_b32 v126, v61, v110
	ds_bpermute_b32 v127, v61, v111
	ds_bpermute_b32 v128, v61, v112
	ds_bpermute_b32 v129, v61, v113
	ds_bpermute_b32 v130, v61, v114
	ds_bpermute_b32 v131, v61, v115
	ds_bpermute_b32 v132, v61, v116
	ds_bpermute_b32 v133, v61, v117
	s_waitcnt lgkmcnt(0)
	v_pk_add_f32 v[110:111], v[110:111], v[126:127]
	v_pk_add_f32 v[112:113], v[112:113], v[128:129]
	v_pk_add_f32 v[114:115], v[114:115], v[130:131]
	v_pk_add_f32 v[116:117], v[116:117], v[132:133]
	ds_bpermute_b32 v134, v61, v118
	ds_bpermute_b32 v135, v61, v119
	ds_bpermute_b32 v136, v61, v120
	ds_bpermute_b32 v137, v61, v121
	ds_bpermute_b32 v138, v61, v122
	ds_bpermute_b32 v139, v61, v123
	ds_bpermute_b32 v140, v61, v124
	ds_bpermute_b32 v141, v61, v125
	s_waitcnt lgkmcnt(0)
	v_pk_add_f32 v[118:119], v[118:119], v[134:135]
	v_pk_add_f32 v[120:121], v[120:121], v[136:137]
	v_pk_add_f32 v[122:123], v[122:123], v[138:139]
	v_pk_add_f32 v[124:125], v[124:125], v[140:141]
	v_lshrrev_b32_e32 v142, 5, v200
	v_lshlrev_b32_e32 v142, 3, v142
	s_and_saveexec_b64 s[0:1], vcc
	ds_write_b64 v142, v[110:111] offset:1024
	ds_write_b64 v142, v[112:113] offset:1152
	ds_write_b64 v142, v[114:115] offset:1280
	ds_write_b64 v142, v[116:117] offset:1408
	ds_write_b64 v142, v[118:119] offset:1536
	ds_write_b64 v142, v[120:121] offset:1664
	ds_write_b64 v142, v[122:123] offset:1792
	ds_write_b64 v142, v[124:125] offset:1920
	s_or_b64 exec, exec, s[0:1]
	s_add_i32 s12, s12, s7
	v_or_b32_e32 v72, s6, v68
	s_movk_i32 s0, 0x3500
	v_lshl_or_b32 v18, v54, 2, s12
	s_waitcnt lgkmcnt(1)
	v_mul_lo_u32 v20, v72, s0
	v_readlane_b32 s0, v252, 53
	v_ashrrev_i32_e32 v19, 31, v18
	s_waitcnt lgkmcnt(0)
	v_mov_b32_e32 v21, v1
	v_readlane_b32 s1, v252, 54
	v_lshlrev_b64 v[66:67], 1, v[18:19]
	v_readlane_b32 s40, v250, 6
	v_lshl_add_u64 v[20:21], v[20:21], 1, s[0:1]
	v_lshl_add_u64 v[20:21], v[20:21], 0, v[66:67]
	v_add_co_u32_e32 v22, vcc, 0x1000, v20
	s_lshl_b64 s[0:1], s[76:77], 9
	s_nop 0
	v_addc_co_u32_e32 v23, vcc, 0, v21, vcc
	s_waitcnt vmcnt(0)
	v_mov_b32_e32 v62, v144
	v_mov_b32_e32 v63, v145
	v_add_co_u32_e32 v22, vcc, 0x2000, v20
	v_readlane_b32 s41, v250, 7
	s_nop 0
	v_addc_co_u32_e32 v23, vcc, 0, v21, vcc
	v_mov_b32_e32 v64, v146
	v_mov_b32_e32 v65, v147
	v_add_co_u32_e32 v22, vcc, 0x6b000, v20
	s_add_u32 s0, s40, s0
	s_nop 0
	v_addc_co_u32_e32 v23, vcc, 0, v21, vcc
	v_mov_b32_e32 v58, v148
	v_mov_b32_e32 v59, v149
	v_add_co_u32_e32 v22, vcc, 0x6c000, v20
	v_mul_u32_u24_e32 v26, 0x110, v68
	s_nop 0
	v_addc_co_u32_e32 v23, vcc, 0, v21, vcc
	v_mov_b32_e32 v60, v150
	v_mov_b32_e32 v61, v151
	v_add_co_u32_e32 v22, vcc, 0xd5000, v20
	s_addc_u32 s1, s41, s1
	s_nop 0
	v_addc_co_u32_e32 v23, vcc, 0, v21, vcc
	v_mov_b32_e32 v54, v152
	v_mov_b32_e32 v55, v153
	v_add_co_u32_e32 v22, vcc, 0xd6000, v20
	v_add3_u32 v0, 0, v0, v26
	s_nop 0
	v_addc_co_u32_e32 v23, vcc, 0, v21, vcc
	v_mov_b32_e32 v56, v154
	v_mov_b32_e32 v57, v155
	v_add_co_u32_e32 v22, vcc, 0x13f000, v20
	v_or_b32_e32 v106, 16, v68
	s_nop 0
	v_addc_co_u32_e32 v23, vcc, 0, v21, vcc
	v_mov_b32_e32 v50, v156
	v_mov_b32_e32 v51, v157
	v_add_co_u32_e32 v22, vcc, 0x140000, v20
	v_or_b32_e32 v107, 32, v68
	s_nop 0
	v_addc_co_u32_e32 v23, vcc, 0, v21, vcc
	v_mov_b32_e32 v52, v158
	v_mov_b32_e32 v53, v159
	v_add_co_u32_e32 v22, vcc, 0x1a9000, v20
	v_or_b32_e32 v108, 48, v68
	s_nop 0
	v_addc_co_u32_e32 v23, vcc, 0, v21, vcc
	v_mov_b32_e32 v46, v160
	v_mov_b32_e32 v47, v161
	v_add_co_u32_e32 v22, vcc, 0x1aa000, v20
	v_or_b32_e32 v109, 64, v68
	s_nop 0
	v_addc_co_u32_e32 v23, vcc, 0, v21, vcc
	v_mov_b32_e32 v48, v162
	v_mov_b32_e32 v49, v163
	v_add_co_u32_e32 v22, vcc, 0x213000, v20
	v_readlane_b32 s42, v250, 8
	s_nop 0
	v_addc_co_u32_e32 v23, vcc, 0, v21, vcc
	v_mov_b32_e32 v42, v164
	v_mov_b32_e32 v43, v165
	v_add_co_u32_e32 v22, vcc, 0x214000, v20
	v_readlane_b32 s43, v250, 9
	s_nop 0
	v_addc_co_u32_e32 v23, vcc, 0, v21, vcc
	v_mov_b32_e32 v44, v166
	v_mov_b32_e32 v45, v167
	v_add_co_u32_e32 v22, vcc, 0x27d000, v20
	s_nop 1
	v_addc_co_u32_e32 v23, vcc, 0, v21, vcc
	v_mov_b32_e32 v38, v168
	v_mov_b32_e32 v39, v169
	v_add_co_u32_e32 v22, vcc, 0x27e000, v20
	s_nop 1
	v_addc_co_u32_e32 v23, vcc, 0, v21, vcc
	v_mov_b32_e32 v40, v170
	v_mov_b32_e32 v41, v171
	v_add_co_u32_e32 v22, vcc, 0x2e7000, v20
	s_nop 1
	v_addc_co_u32_e32 v23, vcc, 0, v21, vcc
	v_add_co_u32_e32 v20, vcc, 0x2e8000, v20
	v_mov_b32_e32 v34, v172
	v_mov_b32_e32 v35, v173
	s_nop 0
	v_addc_co_u32_e32 v21, vcc, 0, v21, vcc
	v_mov_b32_e32 v36, v174
	v_mov_b32_e32 v37, v175
	v_lshlrev_b64 v[22:23], 2, v[18:19]
	v_lshlrev_b32_e32 v20, 2, v68
	v_lshl_add_u64 v[18:19], s[8:9], 0, v[22:23]
	v_lshl_add_u64 v[22:23], s[10:11], 0, v[22:23]
	v_mov_b32_e32 v104, v178
	v_mov_b32_e32 v105, v179
	v_mov_b32_e32 v75, v180
	v_mov_b32_e32 v74, v181
	v_mov_b32_e32 v73, v182
	v_mov_b32_e32 v71, v183
	v_mov_b32_e32 v70, v184
	v_mov_b32_e32 v69, v185
	v_readlane_b32 s0, v252, 55
	v_mov_b32_e32 v18, v186
	v_mov_b32_e32 v19, v187
	v_mov_b32_e32 v20, v188
	v_mov_b32_e32 v21, v189
	v_readlane_b32 s1, v252, 56
	v_mov_b32_e32 v22, v190
	v_mov_b32_e32 v23, v191
	v_mov_b32_e32 v24, v192
	v_mov_b32_e32 v25, v193
	s_barrier
	ds_read_b128 v[26:29], v0 offset:2048
	ds_read_b128 v[30:33], v0 offset:6400
	ds_read_b128 v[76:79], v0 offset:10752
	ds_read_b128 v[80:83], v0 offset:15104
	ds_read_b128 v[84:87], v0 offset:19456
	ds_read_b128 v[88:91], v0 offset:23808
	ds_read_b128 v[92:95], v0 offset:28160
	ds_read_b128 v[96:99], v0 offset:32512
	s_waitcnt lgkmcnt(7)
	v_mfma_f32_16x16x32_bf16 v[26:29], v[14:17], v[26:29], 0
	v_lshl_add_u64 v[66:67], s[0:1], 0, v[66:67]
	s_mov_b64 s[0:1], 0
	s_waitcnt lgkmcnt(6)
	v_mfma_f32_16x16x32_bf16 v[30:33], v[14:17], v[30:33], 0
	s_waitcnt lgkmcnt(5)
	v_mfma_f32_16x16x32_bf16 v[76:79], v[14:17], v[76:79], 0
	s_waitcnt lgkmcnt(4)
	v_mfma_f32_16x16x32_bf16 v[80:83], v[14:17], v[80:83], 0
	s_waitcnt lgkmcnt(3)
	v_mfma_f32_16x16x32_bf16 v[84:87], v[14:17], v[84:87], 0
	s_waitcnt lgkmcnt(2)
	v_mfma_f32_16x16x32_bf16 v[88:91], v[14:17], v[88:91], 0
	s_waitcnt lgkmcnt(1)
	v_mfma_f32_16x16x32_bf16 v[92:95], v[14:17], v[92:95], 0
	s_waitcnt lgkmcnt(0)
	v_mfma_f32_16x16x32_bf16 v[14:17], v[14:17], v[96:99], 0
	ds_read_b128 v[96:99], v0 offset:2112
	s_waitcnt lgkmcnt(0)
	v_mfma_f32_16x16x32_bf16 v[26:29], v[10:13], v[96:99], v[26:29]
	ds_read_b128 v[96:99], v0 offset:6464
	s_waitcnt lgkmcnt(0)
	v_mfma_f32_16x16x32_bf16 v[30:33], v[10:13], v[96:99], v[30:33]
	ds_read_b128 v[96:99], v0 offset:10816
	s_waitcnt lgkmcnt(0)
	v_mfma_f32_16x16x32_bf16 v[76:79], v[10:13], v[96:99], v[76:79]
	ds_read_b128 v[96:99], v0 offset:15168
	s_waitcnt lgkmcnt(0)
	v_mfma_f32_16x16x32_bf16 v[80:83], v[10:13], v[96:99], v[80:83]
	ds_read_b128 v[96:99], v0 offset:19520
	s_waitcnt lgkmcnt(0)
	v_mfma_f32_16x16x32_bf16 v[84:87], v[10:13], v[96:99], v[84:87]
	ds_read_b128 v[96:99], v0 offset:23872
	s_waitcnt lgkmcnt(0)
	v_mfma_f32_16x16x32_bf16 v[88:91], v[10:13], v[96:99], v[88:91]
	ds_read_b128 v[96:99], v0 offset:28224
	s_waitcnt lgkmcnt(0)
	v_mfma_f32_16x16x32_bf16 v[92:95], v[10:13], v[96:99], v[92:95]
	ds_read_b128 v[96:99], v0 offset:32576
	s_waitcnt lgkmcnt(0)
	v_mfma_f32_16x16x32_bf16 v[10:13], v[10:13], v[96:99], v[14:17]
	s_nop 2
	ds_read_b128 v[14:17], v0 offset:2176
	s_waitcnt lgkmcnt(0)
	v_mfma_f32_16x16x32_bf16 v[14:17], v[6:9], v[14:17], v[26:29]
	s_nop 2
	ds_read_b128 v[26:29], v0 offset:6528
	s_waitcnt lgkmcnt(0)
	v_mfma_f32_16x16x32_bf16 v[26:29], v[6:9], v[26:29], v[30:33]
	s_nop 2
	ds_read_b128 v[30:33], v0 offset:10880
	s_waitcnt lgkmcnt(0)
	v_mfma_f32_16x16x32_bf16 v[30:33], v[6:9], v[30:33], v[76:79]
	s_nop 2
	ds_read_b128 v[76:79], v0 offset:15232
	s_waitcnt lgkmcnt(0)
	v_mfma_f32_16x16x32_bf16 v[76:79], v[6:9], v[76:79], v[80:83]
	s_nop 2
	ds_read_b128 v[80:83], v0 offset:19584
	s_waitcnt lgkmcnt(0)
	v_mfma_f32_16x16x32_bf16 v[80:83], v[6:9], v[80:83], v[84:87]
	s_nop 2
	ds_read_b128 v[84:87], v0 offset:23936
	s_waitcnt lgkmcnt(0)
	v_mfma_f32_16x16x32_bf16 v[84:87], v[6:9], v[84:87], v[88:91]
	s_nop 2
	ds_read_b128 v[88:91], v0 offset:28288
	s_waitcnt lgkmcnt(0)
	v_mfma_f32_16x16x32_bf16 v[88:91], v[6:9], v[88:91], v[92:95]
	s_nop 2
	ds_read_b128 v[92:95], v0 offset:32640
	s_waitcnt lgkmcnt(0)
	v_mfma_f32_16x16x32_bf16 v[92:95], v[6:9], v[92:95], v[10:13]
	ds_read_b128 v[6:9], v0 offset:2240
	s_waitcnt lgkmcnt(0)
	v_mfma_f32_16x16x32_bf16 v[96:99], v[2:5], v[6:9], v[14:17]
	ds_read_b128 v[6:9], v0 offset:6592
	s_waitcnt lgkmcnt(0)
	v_mfma_f32_16x16x32_bf16 v[100:103], v[2:5], v[6:9], v[26:29]
	ds_read_b128 v[6:9], v0 offset:10944
	s_waitcnt lgkmcnt(0)
	v_mfma_f32_16x16x32_bf16 v[30:33], v[2:5], v[6:9], v[30:33]
	ds_read_b128 v[6:9], v0 offset:15296
	ds_read_b128 v[10:13], v0 offset:19648
	s_waitcnt lgkmcnt(1)
	v_mfma_f32_16x16x32_bf16 v[26:29], v[2:5], v[6:9], v[76:79]
	ds_read_b128 v[6:9], v0 offset:24000
	s_nop 1
	ds_read_b128 v[76:79], v0 offset:28352
	s_waitcnt lgkmcnt(2)
	v_mfma_f32_16x16x32_bf16 v[14:17], v[2:5], v[10:13], v[80:83]
	s_nop 2
	ds_read_b128 v[80:83], v0 offset:32704
	v_lshl_add_u32 v0, v68, 3, 0
	s_waitcnt lgkmcnt(2)
	v_mfma_f32_16x16x32_bf16 v[10:13], v[2:5], v[6:9], v[84:87]
	s_waitcnt lgkmcnt(1)
	v_mfma_f32_16x16x32_bf16 v[6:9], v[2:5], v[76:79], v[88:91]
	ds_read_b64 v[76:77], v0 offset:1024
	s_waitcnt vmcnt(25)
	v_lshlrev_b32_e32 v0, 16, v62
	v_and_b32_e32 v62, 0xffff0000, v62
	v_or_b32_e32 v84, 0x50, v68
	v_or_b32_e32 v85, 0x60, v68
	s_waitcnt lgkmcnt(0)
	v_sub_f32_e32 v78, v96, v76
	s_waitcnt vmcnt(0)
	v_mul_f32_e32 v79, v22, v77
	v_fmac_f32_e32 v79, v18, v78
	v_add_f32_e32 v78, v104, v79
	v_mul_f32_e32 v0, v78, v0
	v_lshlrev_b32_e32 v78, 16, v64
	v_mul_f32_e32 v0, v0, v78
	v_sub_f32_e32 v78, v97, v76
	v_mul_f32_e32 v79, v23, v77
	v_fmac_f32_e32 v79, v19, v78
	v_add_f32_e32 v78, v104, v79
	v_mul_f32_e32 v62, v78, v62
	v_sub_f32_e32 v78, v98, v76
	v_mul_f32_e32 v79, v24, v77
	v_sub_f32_e32 v76, v99, v76
	v_mul_f32_e32 v77, v25, v77
	v_and_b32_e32 v64, 0xffff0000, v64
	v_fmac_f32_e32 v79, v20, v78
	v_fmac_f32_e32 v77, v21, v76
	v_mul_f32_e32 v62, v62, v64
	v_lshlrev_b32_e32 v64, 16, v63
	v_add_f32_e32 v78, v104, v79
	v_and_b32_e32 v63, 0xffff0000, v63
	v_add_f32_e32 v76, v104, v77
	v_mul_f32_e32 v64, v78, v64
	v_lshlrev_b32_e32 v78, 16, v65
	v_mul_f32_e32 v63, v76, v63
	v_and_b32_e32 v65, 0xffff0000, v65
	v_mul_f32_e32 v64, v64, v78
	v_mul_f32_e32 v63, v63, v65
	v_cvt_pk_bf16_f32 v62, v0, v62
	v_lshl_add_u32 v0, v106, 3, 0
	v_cvt_pk_bf16_f32 v63, v64, v63
	ds_read_b64 v[64:65], v0 offset:1024
	v_lshlrev_b32_e32 v0, 11, v72
	v_lshl_add_u64 v[76:77], v[66:67], 0, v[0:1]
	global_store_dwordx2 v[76:77], v[62:63], off
	v_lshlrev_b32_e32 v0, 16, v58
	s_waitcnt lgkmcnt(0)
	v_sub_f32_e32 v62, v100, v64
	v_mul_f32_e32 v63, v22, v65
	v_fmac_f32_e32 v63, v18, v62
	v_add_f32_e32 v62, v105, v63
	v_mul_f32_e32 v0, v62, v0
	v_lshlrev_b32_e32 v62, 16, v60
	v_mul_f32_e32 v0, v0, v62
	v_sub_f32_e32 v62, v101, v64
	v_mul_f32_e32 v63, v23, v65
	v_fmac_f32_e32 v63, v19, v62
	v_and_b32_e32 v58, 0xffff0000, v58
	v_add_f32_e32 v62, v105, v63
	v_mul_f32_e32 v58, v62, v58
	v_sub_f32_e32 v62, v102, v64
	v_mul_f32_e32 v63, v24, v65
	v_and_b32_e32 v60, 0xffff0000, v60
	v_fmac_f32_e32 v63, v20, v62
	v_mul_f32_e32 v58, v58, v60
	v_lshlrev_b32_e32 v60, 16, v59
	v_add_f32_e32 v62, v105, v63
	v_mul_f32_e32 v60, v62, v60
	v_lshlrev_b32_e32 v62, 16, v61
	v_mul_f32_e32 v60, v60, v62
	v_sub_f32_e32 v62, v103, v64
	v_mul_f32_e32 v63, v25, v65
	v_fmac_f32_e32 v63, v21, v62
	v_and_b32_e32 v59, 0xffff0000, v59
	v_add_f32_e32 v62, v105, v63
	v_mul_f32_e32 v59, v62, v59
	v_and_b32_e32 v61, 0xffff0000, v61
	v_mul_f32_e32 v59, v59, v61
	v_cvt_pk_bf16_f32 v58, v0, v58
	v_cvt_pk_bf16_f32 v59, v60, v59
	v_lshl_add_u32 v60, v107, 3, 0
	ds_read_b64 v[60:61], v60 offset:1024
	v_or_b32_e32 v0, s6, v106
	v_lshlrev_b32_e32 v0, 11, v0
	v_lshl_add_u64 v[62:63], v[66:67], 0, v[0:1]
	global_store_dwordx2 v[62:63], v[58:59], off
	s_waitcnt lgkmcnt(0)
	v_sub_f32_e32 v30, v30, v60
	v_mul_f32_e32 v58, v22, v61
	v_fmac_f32_e32 v58, v18, v30
	v_lshlrev_b32_e32 v0, 16, v54
	v_add_f32_e32 v30, v75, v58
	v_mul_f32_e32 v0, v30, v0
	v_lshlrev_b32_e32 v30, 16, v56
	v_mul_f32_e32 v0, v0, v30
	v_and_b32_e32 v30, 0xffff0000, v54
	v_sub_f32_e32 v31, v31, v60
	v_mul_f32_e32 v54, v23, v61
	v_fmac_f32_e32 v54, v19, v31
	v_add_f32_e32 v31, v75, v54
	v_sub_f32_e32 v32, v32, v60
	v_mul_f32_e32 v54, v24, v61
	v_mul_f32_e32 v30, v31, v30
	v_and_b32_e32 v31, 0xffff0000, v56
	v_fmac_f32_e32 v54, v20, v32
	v_mul_f32_e32 v30, v30, v31
	v_lshlrev_b32_e32 v31, 16, v55
	v_add_f32_e32 v32, v75, v54
	v_sub_f32_e32 v33, v33, v60
	v_mul_f32_e32 v54, v25, v61
	v_mul_f32_e32 v31, v32, v31
	v_lshlrev_b32_e32 v32, 16, v57
	v_fmac_f32_e32 v54, v21, v33
	v_mul_f32_e32 v31, v31, v32
	v_and_b32_e32 v32, 0xffff0000, v55
	v_add_f32_e32 v33, v75, v54
	v_mul_f32_e32 v32, v33, v32
	v_and_b32_e32 v33, 0xffff0000, v57
	v_mul_f32_e32 v32, v32, v33
	v_cvt_pk_bf16_f32 v30, v0, v30
	v_cvt_pk_bf16_f32 v31, v31, v32
	v_lshl_add_u32 v32, v108, 3, 0
	ds_read_b64 v[32:33], v32 offset:1024
	v_or_b32_e32 v0, s6, v107
	v_lshlrev_b32_e32 v0, 11, v0
	v_lshl_add_u64 v[54:55], v[66:67], 0, v[0:1]
	global_store_dwordx2 v[54:55], v[30:31], off
	s_waitcnt lgkmcnt(0)
	v_sub_f32_e32 v26, v26, v32
	v_mul_f32_e32 v30, v22, v33
	v_fmac_f32_e32 v30, v18, v26
	v_lshlrev_b32_e32 v0, 16, v50
	v_add_f32_e32 v26, v74, v30
	v_sub_f32_e32 v27, v27, v32
	v_mul_f32_e32 v30, v23, v33
	v_mul_f32_e32 v0, v26, v0
	v_lshlrev_b32_e32 v26, 16, v52
	v_fmac_f32_e32 v30, v19, v27
	v_mul_f32_e32 v0, v0, v26
	v_and_b32_e32 v26, 0xffff0000, v50
	v_add_f32_e32 v27, v74, v30
	v_sub_f32_e32 v28, v28, v32
	v_mul_f32_e32 v30, v24, v33
	v_mul_f32_e32 v26, v27, v26
	v_and_b32_e32 v27, 0xffff0000, v52
	v_fmac_f32_e32 v30, v20, v28
	v_mul_f32_e32 v26, v26, v27
	v_lshlrev_b32_e32 v27, 16, v51
	v_add_f32_e32 v28, v74, v30
	v_sub_f32_e32 v29, v29, v32
	v_mul_f32_e32 v30, v25, v33
	v_mul_f32_e32 v27, v28, v27
	v_lshlrev_b32_e32 v28, 16, v53
	v_fmac_f32_e32 v30, v21, v29
	v_mul_f32_e32 v27, v27, v28
	v_and_b32_e32 v28, 0xffff0000, v51
	v_add_f32_e32 v29, v74, v30
	v_mul_f32_e32 v28, v29, v28
	v_and_b32_e32 v29, 0xffff0000, v53
	v_mul_f32_e32 v28, v28, v29
	v_cvt_pk_bf16_f32 v26, v0, v26
	v_cvt_pk_bf16_f32 v27, v27, v28
	v_lshl_add_u32 v28, v109, 3, 0
	ds_read_b64 v[28:29], v28 offset:1024
	v_or_b32_e32 v0, s6, v108
	v_lshlrev_b32_e32 v0, 11, v0
	v_lshl_add_u64 v[30:31], v[66:67], 0, v[0:1]
	global_store_dwordx2 v[30:31], v[26:27], off
	s_waitcnt lgkmcnt(0)
	v_sub_f32_e32 v14, v14, v28
	v_mul_f32_e32 v26, v22, v29
	v_fmac_f32_e32 v26, v18, v14
	v_lshlrev_b32_e32 v0, 16, v46
	v_add_f32_e32 v14, v73, v26
	v_sub_f32_e32 v15, v15, v28
	v_mul_f32_e32 v26, v23, v29
	v_mul_f32_e32 v0, v14, v0
	v_lshlrev_b32_e32 v14, 16, v48
	v_fmac_f32_e32 v26, v19, v15
	v_mul_f32_e32 v0, v0, v14
	v_and_b32_e32 v14, 0xffff0000, v46
	v_add_f32_e32 v15, v73, v26
	v_sub_f32_e32 v16, v16, v28
	v_mul_f32_e32 v26, v24, v29
	v_mul_f32_e32 v14, v15, v14
	v_and_b32_e32 v15, 0xffff0000, v48
	v_fmac_f32_e32 v26, v20, v16
	v_mul_f32_e32 v14, v14, v15
	v_lshlrev_b32_e32 v15, 16, v47
	v_add_f32_e32 v16, v73, v26
	v_sub_f32_e32 v17, v17, v28
	v_mul_f32_e32 v26, v25, v29
	v_mul_f32_e32 v15, v16, v15
	v_lshlrev_b32_e32 v16, 16, v49
	v_fmac_f32_e32 v26, v21, v17
	v_mul_f32_e32 v15, v15, v16
	v_and_b32_e32 v16, 0xffff0000, v47
	v_add_f32_e32 v17, v73, v26
	v_mul_f32_e32 v16, v17, v16
	v_and_b32_e32 v17, 0xffff0000, v49
	v_mul_f32_e32 v16, v16, v17
	v_cvt_pk_bf16_f32 v14, v0, v14
	v_cvt_pk_bf16_f32 v15, v15, v16
	v_lshl_add_u32 v16, v84, 3, 0
	ds_read_b64 v[16:17], v16 offset:1024
	v_or_b32_e32 v0, s6, v109
	v_lshlrev_b32_e32 v0, 11, v0
	v_lshl_add_u64 v[26:27], v[66:67], 0, v[0:1]
	global_store_dwordx2 v[26:27], v[14:15], off
	s_waitcnt lgkmcnt(0)
	v_sub_f32_e32 v10, v10, v16
	v_mul_f32_e32 v14, v22, v17
	v_fmac_f32_e32 v14, v18, v10
	v_lshlrev_b32_e32 v0, 16, v42
	v_add_f32_e32 v10, v71, v14
	v_sub_f32_e32 v11, v11, v16
	v_mul_f32_e32 v14, v23, v17
	v_mul_f32_e32 v0, v10, v0
	v_lshlrev_b32_e32 v10, 16, v44
	v_fmac_f32_e32 v14, v19, v11
	v_mul_f32_e32 v0, v0, v10
	v_and_b32_e32 v10, 0xffff0000, v42
	v_add_f32_e32 v11, v71, v14
	v_sub_f32_e32 v12, v12, v16
	v_mul_f32_e32 v14, v24, v17
	v_mul_f32_e32 v10, v11, v10
	v_and_b32_e32 v11, 0xffff0000, v44
	v_fmac_f32_e32 v14, v20, v12
	v_mul_f32_e32 v10, v10, v11
	v_lshlrev_b32_e32 v11, 16, v43
	v_add_f32_e32 v12, v71, v14
	v_sub_f32_e32 v13, v13, v16
	v_mul_f32_e32 v14, v25, v17
	v_mul_f32_e32 v11, v12, v11
	v_lshlrev_b32_e32 v12, 16, v45
	v_fmac_f32_e32 v14, v21, v13
	v_mul_f32_e32 v11, v11, v12
	v_and_b32_e32 v12, 0xffff0000, v43
	v_add_f32_e32 v13, v71, v14
	v_mul_f32_e32 v12, v13, v12
	v_and_b32_e32 v13, 0xffff0000, v45
	v_mul_f32_e32 v12, v12, v13
	v_cvt_pk_bf16_f32 v10, v0, v10
	v_cvt_pk_bf16_f32 v11, v11, v12
	v_lshl_add_u32 v12, v85, 3, 0
	ds_read_b64 v[12:13], v12 offset:1024
	v_or_b32_e32 v0, s6, v84
	v_lshlrev_b32_e32 v0, 11, v0
	v_lshl_add_u64 v[14:15], v[66:67], 0, v[0:1]
	global_store_dwordx2 v[14:15], v[10:11], off
	s_waitcnt lgkmcnt(0)
	v_sub_f32_e32 v6, v6, v12
	v_mul_f32_e32 v10, v22, v13
	v_fmac_f32_e32 v10, v18, v6
	v_lshlrev_b32_e32 v0, 16, v38
	v_add_f32_e32 v6, v70, v10
	v_sub_f32_e32 v7, v7, v12
	v_mul_f32_e32 v10, v23, v13
	v_mul_f32_e32 v0, v6, v0
	v_lshlrev_b32_e32 v6, 16, v40
	v_fmac_f32_e32 v10, v19, v7
	v_mul_f32_e32 v0, v0, v6
	v_and_b32_e32 v6, 0xffff0000, v38
	v_add_f32_e32 v7, v70, v10
	v_sub_f32_e32 v8, v8, v12
	v_mul_f32_e32 v10, v24, v13
	v_mul_f32_e32 v6, v7, v6
	v_and_b32_e32 v7, 0xffff0000, v40
	v_fmac_f32_e32 v10, v20, v8
	v_mul_f32_e32 v6, v6, v7
	v_lshlrev_b32_e32 v7, 16, v39
	v_add_f32_e32 v8, v70, v10
	v_sub_f32_e32 v9, v9, v12
	v_mul_f32_e32 v10, v25, v13
	v_mul_f32_e32 v7, v8, v7
	v_lshlrev_b32_e32 v8, 16, v41
	v_fmac_f32_e32 v10, v21, v9
	v_mul_f32_e32 v7, v7, v8
	v_and_b32_e32 v8, 0xffff0000, v39
	v_add_f32_e32 v9, v70, v10
	v_mul_f32_e32 v8, v9, v8
	v_and_b32_e32 v9, 0xffff0000, v41
	v_or_b32_e32 v68, 0x70, v68
	v_mul_f32_e32 v8, v8, v9
	v_cvt_pk_bf16_f32 v6, v0, v6
	v_cvt_pk_bf16_f32 v7, v7, v8
	v_lshl_add_u32 v8, v68, 3, 0
	ds_read_b64 v[8:9], v8 offset:1024
	v_mfma_f32_16x16x32_bf16 v[2:5], v[2:5], v[80:83], v[92:95]
	v_or_b32_e32 v0, s6, v85
	v_lshlrev_b32_e32 v0, 11, v0
	v_lshl_add_u64 v[10:11], v[66:67], 0, v[0:1]
	global_store_dwordx2 v[10:11], v[6:7], off
	s_waitcnt lgkmcnt(0)
	v_mul_f32_e32 v6, v22, v9
	s_nop 1
	v_sub_f32_e32 v2, v2, v8
	v_fmac_f32_e32 v6, v18, v2
	v_lshlrev_b32_e32 v0, 16, v34
	v_add_f32_e32 v2, v69, v6
	v_sub_f32_e32 v3, v3, v8
	v_mul_f32_e32 v6, v23, v9
	v_mul_f32_e32 v0, v2, v0
	v_lshlrev_b32_e32 v2, 16, v36
	v_fmac_f32_e32 v6, v19, v3
	v_mul_f32_e32 v0, v0, v2
	v_and_b32_e32 v2, 0xffff0000, v34
	v_add_f32_e32 v3, v69, v6
	v_sub_f32_e32 v4, v4, v8
	v_mul_f32_e32 v6, v24, v9
	v_mul_f32_e32 v2, v3, v2
	v_and_b32_e32 v3, 0xffff0000, v36
	v_fmac_f32_e32 v6, v20, v4
	v_mul_f32_e32 v2, v2, v3
	v_lshlrev_b32_e32 v3, 16, v35
	v_add_f32_e32 v4, v69, v6
	v_sub_f32_e32 v5, v5, v8
	v_mul_f32_e32 v6, v25, v9
	v_mul_f32_e32 v3, v4, v3
	v_lshlrev_b32_e32 v4, 16, v37
	v_fmac_f32_e32 v6, v21, v5
	v_mul_f32_e32 v3, v3, v4
	v_and_b32_e32 v4, 0xffff0000, v35
	v_add_f32_e32 v5, v69, v6
	v_mul_f32_e32 v4, v5, v4
	v_and_b32_e32 v5, 0xffff0000, v37
	v_cvt_pk_bf16_f32 v2, v0, v2
	v_or_b32_e32 v0, s6, v68
	v_mul_f32_e32 v4, v4, v5
	v_lshlrev_b32_e32 v0, 11, v0
	v_cvt_pk_bf16_f32 v3, v3, v4
	v_lshl_add_u64 v[4:5], v[66:67], 0, v[0:1]
	global_store_dwordx2 v[4:5], v[2:3], off
	s_barrier
